# FFN1/FFN2 up epilogue: per-row ssq loads for the next unit issued one unit ahead (before the stores); epilogue no longer opens with vmcnt(0)
# baseline (speedup 1.0000x reference)
; #define PG8_STAGE(bufoff, gbase, voff) do { _Pragma("unroll") for (int _i = 0; _i < 2; ++_i) \
;         __builtin_amdgcn_global_load_lds((const unsigned*)((const char*)(gbase) + (voff)[_i]), (PG8_LAS unsigned*)(lds + (bufoff) + ldsw + _i * 8192), 16, 0, 0); } while (0)
; #define PG8_WAIT_V(n) asm volatile("s_waitcnt vmcnt(" #n ")" ::: "memory")
; #define PG8_BAR __builtin_amdgcn_s_barrier()
; template <class Epi, class Sched, bool ALIGN_EPI = false, bool SP2 = false>
; __device__ __forceinline__ void gemm_phase(PG8_LAS unsigned char* lds, const Gemm g, const Sched& S, const Epi& E) {
;     ...
;         PG8_WAIT_V(2); PG8_BAR;
;         PG8_STAGE(PG8_SB(1, 0), cB + kstep, voffB); PG8_STAGE(PG8_SA(1, 0), cA + kstep, voffA); PG8_STAGE(PG8_SB(1, 1), cB + hstep + kstep, voffB);
;         PG8_WAIT_V(6); PG8_BAR;
;   DI void operator()(const f32x4 (&acc)[2][2][4][2], const Unit& u, int wr, int wc, int fr, int fq) const {
;     const int row0 = u.pm * 256 + wr * 64 + fr; const int hcol = u.pn * 128 + wc * 32 + 8 * fq;
;     float rs[8];
; #pragma unroll
;     for (int i = 0; i < 8; ++i) rs[i] = ssq[row0 + (i >> 2) * 128 + (i & 3) * 16];
.LBB0_446:
	s_lshl_b32 s4, s4, 5
	s_and_b32 s14, s4, 0x60
	s_mov_b64 s[4:5], 0x80
	s_add_i32 m0, s28, 0x18000
	v_lshl_add_u64 v[6:7], v[6:7], 0, s[4:5]
	s_lshl_b32 s11, s10, 13
	s_lshl_b32 s15, s14, 7
	s_waitcnt vmcnt(2)
	s_barrier
	global_load_lds_dwordx4 v[6:7], off
	v_lshl_add_u64 v[4:5], v[4:5], 0, s[4:5]
	s_add_i32 m0, s28, 0x1a000
	s_add_i32 s35, s28, 0x8000
	s_add_i32 s36, s28, 0xa000
	global_load_lds_dwordx4 v[4:5], off
	v_lshl_add_u64 v[0:1], v[0:1], 0, s[4:5]
	s_mov_b32 m0, s35
	s_add_u32 s12, s22, 0x40080
	global_load_lds_dwordx4 v[0:1], off
	v_lshl_add_u64 v[0:1], v[2:3], 0, s[4:5]
	s_mov_b32 m0, s36
	s_addc_u32 s13, s23, 0
	global_load_lds_dwordx4 v[0:1], off
	s_add_i32 m0, s28, 0x1c000
	v_lshl_add_u64 v[0:1], s[12:13], 0, v[132:133]
	global_load_lds_dwordx4 v[0:1], off
	v_lshl_add_u64 v[0:1], s[12:13], 0, v[128:129]
	s_add_i32 m0, s28, 0x1e000
	s_cmpk_lt_u32 s7, 0x100
	global_load_lds_dwordx4 v[0:1], off
	v_lshrrev_b32_e32 v1, 1, v9
	v_and_b32_e32 v1, 24, v1
	v_and_b32_e32 v0, 15, v9
	v_lshlrev_b32_e32 v2, 1, v1
	v_lshl_or_b32 v150, s10, 6, v0
	v_lshl_or_b32 v0, v0, 6, v2
	v_lshlrev_b32_e32 v2, 2, v9
	v_and_b32_e32 v2, 32, v2
	v_bitop3_b32 v3, v0, s11, v2 bitop3:0xde
	v_bitop3_b32 v151, v0, s15, v2 bitop3:0xde
	v_lshlrev_b32_e32 v0, 14, v13
	v_and_b32_e32 v0, 0xffff8000, v0
	v_or_b32_e32 v152, s14, v1
	v_lshl_add_u32 v0, v12, 11, v0
	v_and_b32_e32 v1, 1, v13
	v_lshl_or_b32 v0, v1, 6, v0
	v_lshl_add_u32 v136, v14, 1, v0
	v_lshlrev_b32_e32 v0, 14, v8
	v_and_b32_e32 v0, 0xffff8000, v0
	s_waitcnt vmcnt(6)
	v_lshl_add_u32 v0, v10, 11, v0
	v_and_b32_e32 v1, 1, v8
	s_cselect_b64 s[10:11], -1, 0
	v_lshl_or_b32 v0, v1, 6, v0
	s_add_i32 s37, 0, 0x10000
	s_add_i32 s38, 0, 0x14000
	s_sext_i32_i16 s9, s6
	v_mov_b32_e32 v137, v133
	v_lshl_add_u32 v138, v11, 1, v0
	v_mov_b32_e32 v139, v133
	v_mov_b64_e32 v[140:141], 0x1600
	v_mov_b64_e32 v[142:143], 0x15ff
	v_add_u32_e32 v153, s37, v151
	v_add_u32_e32 v154, s38, v151
	v_add_u32_e32 v155, 0, v3
	v_mov_b32_e32 v156, 0x358637bd
	s_mov_b32 s39, 0x800000
	s_movk_i32 s40, 0x1600
	s_barrier
	v_lshl_add_u32 v244, s8, 8, v150
	v_ashrrev_i32_e32 v245, 31, v244
	v_lshl_add_u64 v[244:245], v[244:245], 2, s[56:57]
	global_load_dword v236, v[244:245], off
	global_load_dword v237, v[244:245], off offset:64
	global_load_dword v238, v[244:245], off offset:128
	global_load_dword v239, v[244:245], off offset:192
	global_load_dword v240, v[244:245], off offset:512
	global_load_dword v241, v[244:245], off offset:576
	global_load_dword v242, v[244:245], off offset:640
	global_load_dword v243, v[244:245], off offset:704
	s_branch .LBB0_449

; DI float sigmoidf_(float v) { return __builtin_amdgcn_rcpf(1.f + __builtin_amdgcn_exp2f(-v * 1.4426950408889634f)); }
; DI u32x4 pack8(f32x4 a, f32x4 b) { u32x4 w; w.x = cvtpk(a[0], a[1]); w.y = cvtpk(a[2], a[3]); w.z = cvtpk(b[0], b[1]); w.w = cvtpk(b[2], b[3]); return w; }
;   DI void operator()(const f32x4 (&acc)[2][2][4][2], const Unit& u, int wr, int wc, int fr, int fq) const {
;     const int row0 = u.pm * 256 + wr * 64 + fr; const int hcol = u.pn * 128 + wc * 32 + 8 * fq;
;     float rs[8];
; #pragma unroll
;     for (int i = 0; i < 8; ++i) rs[i] = ssq[row0 + (i >> 2) * 128 + (i & 3) * 16];
; #pragma unroll
;     for (int ai = 0; ai < 2; ++ai)
; #pragma unroll
;       for (int m = 0; m < 4; ++m) {
;         const int row = row0 + ai * 128 + m * 16;
;         const float rstd = rsqrtf(rs[ai * 4 + m] * (1.f / DM) + EPSN);
;         f32x4 o[2];
; #pragma unroll
;         for (int n = 0; n < 2; ++n) {
;           const f32x4 a = acc[ai][0][m][n] * rstd, b = acc[ai][1][m][n] * rstd;
; #pragma unroll
;           for (int e = 0; e < 4; ++e) o[n][e] = a[e] * sigmoidf_(a[e]) * b[e];
;         }
;         __builtin_nontemporal_store(pack8(o[0], o[1]), (u32x4*)(H + (size_t)row * DFF + hcol));
.LBB0_455:
	v_lshl_add_u32 v144, s8, 8, v150
	v_ashrrev_i32_e32 v145, 31, v144
	v_lshl_add_u64 v[148:149], v[144:145], 2, s[56:57]
	v_mov_b32_e32 v162, v236
	v_mov_b32_e32 v163, v237
	v_mov_b32_e32 v175, v238
	v_mov_b32_e32 v176, v239
	v_mov_b32_e32 v177, v240
	v_mov_b32_e32 v178, v241
	v_mov_b32_e32 v157, v242
	v_mov_b32_e32 v145, v243
	s_and_b32 vcc_lo, s14, 0xff
	v_lshl_add_u32 v244, vcc_lo, 8, v150
	v_ashrrev_i32_e32 v245, 31, v244
	v_lshl_add_u64 v[244:245], v[244:245], 2, s[56:57]
	global_load_dword v236, v[244:245], off
	global_load_dword v237, v[244:245], off offset:64
	global_load_dword v238, v[244:245], off offset:128
	global_load_dword v239, v[244:245], off offset:192
	global_load_dword v240, v[244:245], off offset:512
	global_load_dword v241, v[244:245], off offset:576
	global_load_dword v242, v[244:245], off offset:640
	global_load_dword v243, v[244:245], off offset:704
	v_lshl_or_b32 v158, s9, 7, v152
	v_readlane_b32 s8, v252, 3
	v_readlane_b32 s9, v252, 4
	v_ashrrev_i32_e32 v159, 31, v158
	v_add_u32_e32 v174, 0x80, v144
	v_mov_b64_e32 v[146:147], s[8:9]
	v_mad_i64_i32 v[160:161], s[8:9], v144, s40, v[146:147]
	v_fmamk_f32 v148, v162, 0x3a800000, v156
	v_fmamk_f32 v149, v163, 0x3a800000, v156
	v_mul_f32_e32 v162, 0x4b800000, v148
	v_cmp_gt_f32_e32 vcc, s39, v148
	v_mul_f32_e32 v163, 0x4b800000, v149
	v_cmp_gt_f32_e64 s[8:9], s39, v149
	v_cndmask_b32_e32 v148, v148, v162, vcc
	v_rsq_f32_e32 v162, v148
	v_cndmask_b32_e64 v149, v149, v163, s[8:9]
	v_rsq_f32_e32 v163, v149
	v_lshlrev_b64 v[148:149], 1, v[158:159]
	v_lshl_add_u64 v[158:159], v[160:161], 0, v[148:149]
	v_mul_f32_e32 v160, 0x45800000, v162
	v_mul_f32_e32 v161, 0x45800000, v163
	v_cndmask_b32_e32 v160, v162, v160, vcc
	v_cndmask_b32_e64 v162, v163, v161, s[8:9]
	v_pk_mul_f32 v[124:125], v[124:125], v[160:161] op_sel_hi:[1,0]
	v_pk_mul_f32 v[126:127], v[126:127], v[160:161] op_sel_hi:[1,0]
	v_pk_mul_f32 v[120:121], v[120:121], v[160:161] op_sel_hi:[1,0]
	v_pk_mul_f32 v[122:123], v[122:123], v[160:161] op_sel_hi:[1,0]
	v_pk_mul_f32 v[112:113], v[112:113], v[160:161] op_sel_hi:[1,0]
	v_pk_mul_f32 v[114:115], v[114:115], v[160:161] op_sel_hi:[1,0]
	v_pk_mul_f32 v[108:109], v[108:109], v[160:161] op_sel_hi:[1,0]
	v_pk_mul_f32 v[110:111], v[110:111], v[160:161] op_sel_hi:[1,0]
	v_pk_mul_f32 v[116:117], v[116:117], v[162:163] op_sel_hi:[1,0]
	v_pk_mul_f32 v[100:101], v[100:101], v[162:163] op_sel_hi:[1,0]
	v_pk_mul_f32 v[118:119], v[118:119], v[162:163] op_sel_hi:[1,0]
	v_mul_f32_e32 v160, 0xbfb8aa3b, v124
	v_mul_f32_e32 v161, 0xbfb8aa3b, v125
	v_mul_f32_e32 v163, 0xbfb8aa3b, v126
	v_mul_f32_e32 v164, 0xbfb8aa3b, v127
	v_mul_f32_e32 v165, 0xbfb8aa3b, v120
	v_mul_f32_e32 v166, 0xbfb8aa3b, v121
	v_mul_f32_e32 v167, 0xbfb8aa3b, v122
	v_mul_f32_e32 v168, 0xbfb8aa3b, v123
	v_mul_f32_e32 v169, 0xbfb8aa3b, v116
	v_exp_f32_e32 v160, v160
	v_exp_f32_e32 v161, v161
	v_exp_f32_e32 v163, v163
	v_exp_f32_e32 v164, v164
	v_exp_f32_e32 v165, v165
	v_exp_f32_e32 v166, v166
	v_exp_f32_e32 v167, v167
	v_exp_f32_e32 v168, v168
	v_exp_f32_e32 v169, v169
	v_add_f32_e32 v160, 1.0, v160
	v_add_f32_e32 v161, 1.0, v161
	v_add_f32_e32 v163, 1.0, v163
	v_add_f32_e32 v173, 1.0, v164
	v_add_f32_e32 v179, 1.0, v165
	v_add_f32_e32 v180, 1.0, v166
	v_add_f32_e32 v181, 1.0, v167
	v_add_f32_e32 v182, 1.0, v168
	v_add_f32_e32 v183, 1.0, v169
	v_rcp_f32_e32 v160, v160
	v_rcp_f32_e32 v161, v161
	v_rcp_f32_e32 v164, v163
	v_rcp_f32_e32 v165, v173
	v_rcp_f32_e32 v166, v179
	v_rcp_f32_e32 v167, v180
	v_rcp_f32_e32 v168, v181
	v_rcp_f32_e32 v169, v182
	v_mul_f32_e32 v171, 0xbfb8aa3b, v118
	v_mul_f32_e32 v172, 0xbfb8aa3b, v119
	v_exp_f32_e32 v171, v171
	v_exp_f32_e32 v172, v172
	v_pk_mul_f32 v[124:125], v[124:125], v[160:161]
	v_pk_mul_f32 v[126:127], v[126:127], v[164:165]
	v_pk_mul_f32 v[120:121], v[120:121], v[166:167]
	v_pk_mul_f32 v[122:123], v[122:123], v[168:169]
	v_pk_mul_f32 v[112:113], v[112:113], v[124:125]
	v_pk_mul_f32 v[114:115], v[114:115], v[126:127]
	v_pk_mul_f32 v[120:121], v[108:109], v[120:121]
	v_pk_mul_f32 v[122:123], v[110:111], v[122:123]
	v_add_f32_e32 v185, 1.0, v171
	v_add_f32_e32 v186, 1.0, v172
	v_cvt_pk_bf16_f32 v108, v112, v113
	v_cvt_pk_bf16_f32 v109, v114, v115
	v_cvt_pk_bf16_f32 v110, v120, v121
	v_cvt_pk_bf16_f32 v111, v122, v123
	v_pk_mul_f32 v[104:105], v[104:105], v[162:163] op_sel_hi:[1,0]
	v_rcp_f32_e32 v172, v185
	v_rcp_f32_e32 v173, v186
	global_store_dwordx4 v[158:159], v[108:111], off nt
	v_mul_f32_e32 v170, 0xbfb8aa3b, v117
	v_pk_mul_f32 v[102:103], v[102:103], v[162:163] op_sel_hi:[1,0]
	v_mul_f32_e32 v110, 0xbfb8aa3b, v104
	v_mul_f32_e32 v111, 0xbfb8aa3b, v105
	v_exp_f32_e32 v110, v110
	v_exp_f32_e32 v111, v111
	v_pk_mul_f32 v[108:109], v[118:119], v[172:173]
	v_pk_mul_f32 v[106:107], v[106:107], v[162:163] op_sel_hi:[1,0]
	v_exp_f32_e32 v170, v170
	v_pk_mul_f32 v[102:103], v[102:103], v[108:109]
	v_add_f32_e32 v108, 1.0, v110
	v_add_f32_e32 v109, 1.0, v111
	v_mul_f32_e32 v110, 0xbfb8aa3b, v106
	v_mul_f32_e32 v111, 0xbfb8aa3b, v107
	v_exp_f32_e32 v110, v110
	v_exp_f32_e32 v111, v111
	v_add_f32_e32 v184, 1.0, v170
	v_rcp_f32_e32 v170, v183
	v_rcp_f32_e32 v171, v184
	v_rcp_f32_e32 v108, v108
	v_rcp_f32_e32 v109, v109
	v_add_f32_e32 v110, 1.0, v110
	v_add_f32_e32 v111, 1.0, v111
	v_rcp_f32_e32 v110, v110
	v_rcp_f32_e32 v111, v111
	v_pk_mul_f32 v[116:117], v[116:117], v[170:171]
	v_pk_mul_f32 v[104:105], v[104:105], v[108:109]
	v_pk_mul_f32 v[96:97], v[96:97], v[162:163] op_sel_hi:[1,0]
	v_pk_mul_f32 v[100:101], v[100:101], v[116:117]
	v_pk_mul_f32 v[104:105], v[96:97], v[104:105]
	v_pk_mul_f32 v[96:97], v[106:107], v[110:111]
	v_pk_mul_f32 v[98:99], v[98:99], v[162:163] op_sel_hi:[1,0]
; DI float sigmoidf_(float v) { return __builtin_amdgcn_rcpf(1.f + __builtin_amdgcn_exp2f(-v * 1.4426950408889634f)); }
; DI u32x4 pack8(f32x4 a, f32x4 b) { u32x4 w; w.x = cvtpk(a[0], a[1]); w.y = cvtpk(a[2], a[3]); w.z = cvtpk(b[0], b[1]); w.w = cvtpk(b[2], b[3]); return w; }
;   DI void operator()(const f32x4 (&acc)[2][2][4][2], const Unit& u, int wr, int wc, int fr, int fq) const {
;     ...
;       for (int m = 0; m < 4; ++m) {
;         const int row = row0 + ai * 128 + m * 16;
;         const float rstd = rsqrtf(rs[ai * 4 + m] * (1.f / DM) + EPSN);
;         f32x4 o[2];
; #pragma unroll
;         for (int n = 0; n < 2; ++n) {
;           const f32x4 a = acc[ai][0][m][n] * rstd, b = acc[ai][1][m][n] * rstd;
; #pragma unroll
;           for (int e = 0; e < 4; ++e) o[n][e] = a[e] * sigmoidf_(a[e]) * b[e];
;         }
;         __builtin_nontemporal_store(pack8(o[0], o[1]), (u32x4*)(H + (size_t)row * DFF + hcol));
	v_or_b32_e32 v108, 16, v144
	v_pk_mul_f32 v[106:107], v[98:99], v[96:97]
	v_cvt_pk_bf16_f32 v96, v100, v101
	v_fmamk_f32 v100, v175, 0x3a800000, v156
	v_mul_f32_e32 v101, 0x4b800000, v100
	v_cmp_gt_f32_e32 vcc, s39, v100
	v_cvt_pk_bf16_f32 v97, v102, v103
	v_cvt_pk_bf16_f32 v98, v104, v105
	v_cndmask_b32_e32 v100, v100, v101, vcc
	v_rsq_f32_e32 v102, v100
	v_mad_i64_i32 v[100:101], s[8:9], v108, s40, v[146:147]
	v_cvt_pk_bf16_f32 v99, v106, v107
	v_mul_f32_e32 v103, 0x45800000, v102
	v_cndmask_b32_e32 v102, v102, v103, vcc
	v_pk_mul_f32 v[92:93], v[92:93], v[102:103] op_sel_hi:[1,0]
	v_lshl_add_u64 v[100:101], v[100:101], 0, v[148:149]
	v_mul_f32_e32 v103, 0xbfb8aa3b, v92
	v_exp_f32_e32 v103, v103
	v_mul_f32_e32 v104, 0xbfb8aa3b, v93
	v_exp_f32_e32 v104, v104
	global_store_dwordx4 v[100:101], v[96:99], off nt
	v_pk_mul_f32 v[94:95], v[94:95], v[102:103] op_sel_hi:[1,0]
	v_pk_mul_f32 v[84:85], v[84:85], v[102:103] op_sel_hi:[1,0]
	v_mul_f32_e32 v98, 0xbfb8aa3b, v94
	v_mul_f32_e32 v99, 0xbfb8aa3b, v95
	v_exp_f32_e32 v98, v98
	v_exp_f32_e32 v99, v99
	v_add_f32_e32 v96, 1.0, v103
	v_add_f32_e32 v97, 1.0, v104
	v_rcp_f32_e32 v96, v96
	v_rcp_f32_e32 v97, v97
	v_add_f32_e32 v98, 1.0, v98
	v_add_f32_e32 v99, 1.0, v99
	v_rcp_f32_e32 v98, v98
	v_rcp_f32_e32 v99, v99
	v_pk_mul_f32 v[92:93], v[92:93], v[96:97]
	v_pk_mul_f32 v[88:89], v[88:89], v[102:103] op_sel_hi:[1,0]
	v_pk_mul_f32 v[84:85], v[84:85], v[92:93]
	v_pk_mul_f32 v[92:93], v[94:95], v[98:99]
	v_mul_f32_e32 v94, 0xbfb8aa3b, v88
	v_mul_f32_e32 v95, 0xbfb8aa3b, v89
	v_exp_f32_e32 v94, v94
	v_exp_f32_e32 v95, v95
	v_pk_mul_f32 v[86:87], v[86:87], v[102:103] op_sel_hi:[1,0]
	v_pk_mul_f32 v[90:91], v[90:91], v[102:103] op_sel_hi:[1,0]
	v_pk_mul_f32 v[86:87], v[86:87], v[92:93]
	v_add_f32_e32 v92, 1.0, v94
	v_add_f32_e32 v93, 1.0, v95
	v_mul_f32_e32 v94, 0xbfb8aa3b, v90
	v_mul_f32_e32 v95, 0xbfb8aa3b, v91
	v_exp_f32_e32 v94, v94
	v_exp_f32_e32 v95, v95
	v_rcp_f32_e32 v92, v92
	v_rcp_f32_e32 v93, v93
	v_add_f32_e32 v94, 1.0, v94
	v_add_f32_e32 v95, 1.0, v95
	v_rcp_f32_e32 v94, v94
	v_rcp_f32_e32 v95, v95
	v_pk_mul_f32 v[88:89], v[88:89], v[92:93]
	v_pk_mul_f32 v[80:81], v[80:81], v[102:103] op_sel_hi:[1,0]
	v_pk_mul_f32 v[82:83], v[82:83], v[102:103] op_sel_hi:[1,0]
	v_pk_mul_f32 v[88:89], v[80:81], v[88:89]
	v_pk_mul_f32 v[80:81], v[90:91], v[94:95]
	v_or_b32_e32 v92, 32, v144
	v_pk_mul_f32 v[90:91], v[82:83], v[80:81]
	v_cvt_pk_bf16_f32 v80, v84, v85
	v_fmamk_f32 v84, v176, 0x3a800000, v156
	v_mul_f32_e32 v85, 0x4b800000, v84
	v_cmp_gt_f32_e32 vcc, s39, v84
	v_cvt_pk_bf16_f32 v81, v86, v87
	v_cvt_pk_bf16_f32 v82, v88, v89
	v_cndmask_b32_e32 v84, v84, v85, vcc
	v_rsq_f32_e32 v86, v84
	v_mad_i64_i32 v[84:85], s[8:9], v92, s40, v[146:147]
	v_cvt_pk_bf16_f32 v83, v90, v91
	v_mul_f32_e32 v87, 0x45800000, v86
	v_cndmask_b32_e32 v86, v86, v87, vcc
	v_pk_mul_f32 v[76:77], v[76:77], v[86:87] op_sel_hi:[1,0]
	v_lshl_add_u64 v[84:85], v[84:85], 0, v[148:149]
	v_mul_f32_e32 v87, 0xbfb8aa3b, v76
	v_exp_f32_e32 v87, v87
	v_mul_f32_e32 v88, 0xbfb8aa3b, v77
	v_exp_f32_e32 v88, v88
	global_store_dwordx4 v[84:85], v[80:83], off nt
	v_pk_mul_f32 v[78:79], v[78:79], v[86:87] op_sel_hi:[1,0]
	v_pk_mul_f32 v[68:69], v[68:69], v[86:87] op_sel_hi:[1,0]
	v_mul_f32_e32 v82, 0xbfb8aa3b, v78
	v_mul_f32_e32 v83, 0xbfb8aa3b, v79
	v_exp_f32_e32 v82, v82
	v_exp_f32_e32 v83, v83
	v_add_f32_e32 v80, 1.0, v87
	v_add_f32_e32 v81, 1.0, v88
	v_rcp_f32_e32 v80, v80
	v_rcp_f32_e32 v81, v81
	v_add_f32_e32 v82, 1.0, v82
	v_add_f32_e32 v83, 1.0, v83
	v_rcp_f32_e32 v82, v82
	v_rcp_f32_e32 v83, v83
	v_pk_mul_f32 v[76:77], v[76:77], v[80:81]
	v_pk_mul_f32 v[72:73], v[72:73], v[86:87] op_sel_hi:[1,0]
	v_pk_mul_f32 v[68:69], v[68:69], v[76:77]
	v_pk_mul_f32 v[76:77], v[78:79], v[82:83]
	v_mul_f32_e32 v78, 0xbfb8aa3b, v72
	v_mul_f32_e32 v79, 0xbfb8aa3b, v73
	v_exp_f32_e32 v78, v78
	v_exp_f32_e32 v79, v79
	v_pk_mul_f32 v[70:71], v[70:71], v[86:87] op_sel_hi:[1,0]
	v_pk_mul_f32 v[74:75], v[74:75], v[86:87] op_sel_hi:[1,0]
	v_pk_mul_f32 v[70:71], v[70:71], v[76:77]
	v_add_f32_e32 v76, 1.0, v78
	v_add_f32_e32 v77, 1.0, v79
	v_mul_f32_e32 v78, 0xbfb8aa3b, v74
	v_mul_f32_e32 v79, 0xbfb8aa3b, v75
	v_exp_f32_e32 v78, v78
	v_exp_f32_e32 v79, v79
	v_rcp_f32_e32 v76, v76
	v_rcp_f32_e32 v77, v77
	v_add_f32_e32 v78, 1.0, v78
	v_add_f32_e32 v79, 1.0, v79
	v_rcp_f32_e32 v78, v78
	v_rcp_f32_e32 v79, v79
	v_pk_mul_f32 v[72:73], v[72:73], v[76:77]
	v_pk_mul_f32 v[64:65], v[64:65], v[86:87] op_sel_hi:[1,0]
	v_pk_mul_f32 v[66:67], v[66:67], v[86:87] op_sel_hi:[1,0]
	v_pk_mul_f32 v[72:73], v[64:65], v[72:73]
	v_pk_mul_f32 v[64:65], v[74:75], v[78:79]
	v_or_b32_e32 v76, 48, v144
	v_pk_mul_f32 v[74:75], v[66:67], v[64:65]
	v_cvt_pk_bf16_f32 v64, v68, v69
	v_fmamk_f32 v68, v177, 0x3a800000, v156
	v_mul_f32_e32 v69, 0x4b800000, v68
	v_cmp_gt_f32_e32 vcc, s39, v68
	v_cvt_pk_bf16_f32 v65, v70, v71
	v_cvt_pk_bf16_f32 v66, v72, v73
	v_cndmask_b32_e32 v68, v68, v69, vcc
	v_rsq_f32_e32 v70, v68
	v_mad_i64_i32 v[68:69], s[8:9], v76, s40, v[146:147]
	v_cvt_pk_bf16_f32 v67, v74, v75
	v_mul_f32_e32 v71, 0x45800000, v70
	v_cndmask_b32_e32 v70, v70, v71, vcc
	v_pk_mul_f32 v[60:61], v[60:61], v[70:71] op_sel_hi:[1,0]
	v_lshl_add_u64 v[68:69], v[68:69], 0, v[148:149]
	v_mul_f32_e32 v71, 0xbfb8aa3b, v60
	v_exp_f32_e32 v71, v71
	v_mul_f32_e32 v72, 0xbfb8aa3b, v61
	v_exp_f32_e32 v72, v72
	global_store_dwordx4 v[68:69], v[64:67], off nt
	v_pk_mul_f32 v[62:63], v[62:63], v[70:71] op_sel_hi:[1,0]
	v_pk_mul_f32 v[52:53], v[52:53], v[70:71] op_sel_hi:[1,0]
	v_mul_f32_e32 v66, 0xbfb8aa3b, v62
	v_mul_f32_e32 v67, 0xbfb8aa3b, v63
	v_exp_f32_e32 v66, v66
	v_exp_f32_e32 v67, v67
; DI float sigmoidf_(float v) { return __builtin_amdgcn_rcpf(1.f + __builtin_amdgcn_exp2f(-v * 1.4426950408889634f)); }
; DI u32x4 pack8(f32x4 a, f32x4 b) { u32x4 w; w.x = cvtpk(a[0], a[1]); w.y = cvtpk(a[2], a[3]); w.z = cvtpk(b[0], b[1]); w.w = cvtpk(b[2], b[3]); return w; }
;   DI void operator()(const f32x4 (&acc)[2][2][4][2], const Unit& u, int wr, int wc, int fr, int fq) const {
;     ...
;       for (int m = 0; m < 4; ++m) {
;         const int row = row0 + ai * 128 + m * 16;
;         const float rstd = rsqrtf(rs[ai * 4 + m] * (1.f / DM) + EPSN);
;         f32x4 o[2];
; #pragma unroll
;         for (int n = 0; n < 2; ++n) {
;           const f32x4 a = acc[ai][0][m][n] * rstd, b = acc[ai][1][m][n] * rstd;
; #pragma unroll
;           for (int e = 0; e < 4; ++e) o[n][e] = a[e] * sigmoidf_(a[e]) * b[e];
;         }
;         __builtin_nontemporal_store(pack8(o[0], o[1]), (u32x4*)(H + (size_t)row * DFF + hcol));
	v_add_f32_e32 v64, 1.0, v71
	v_add_f32_e32 v65, 1.0, v72
	v_rcp_f32_e32 v64, v64
	v_rcp_f32_e32 v65, v65
	v_add_f32_e32 v66, 1.0, v66
	v_add_f32_e32 v67, 1.0, v67
	v_rcp_f32_e32 v66, v66
	v_rcp_f32_e32 v67, v67
	v_pk_mul_f32 v[60:61], v[60:61], v[64:65]
	v_pk_mul_f32 v[56:57], v[56:57], v[70:71] op_sel_hi:[1,0]
	v_pk_mul_f32 v[52:53], v[52:53], v[60:61]
	v_pk_mul_f32 v[60:61], v[62:63], v[66:67]
	v_mul_f32_e32 v62, 0xbfb8aa3b, v56
	v_mul_f32_e32 v63, 0xbfb8aa3b, v57
	v_exp_f32_e32 v62, v62
	v_exp_f32_e32 v63, v63
	v_pk_mul_f32 v[54:55], v[54:55], v[70:71] op_sel_hi:[1,0]
	v_pk_mul_f32 v[58:59], v[58:59], v[70:71] op_sel_hi:[1,0]
	v_pk_mul_f32 v[54:55], v[54:55], v[60:61]
	v_add_f32_e32 v60, 1.0, v62
	v_add_f32_e32 v61, 1.0, v63
	v_mul_f32_e32 v62, 0xbfb8aa3b, v58
	v_mul_f32_e32 v63, 0xbfb8aa3b, v59
	v_exp_f32_e32 v62, v62
	v_exp_f32_e32 v63, v63
	v_rcp_f32_e32 v60, v60
	v_rcp_f32_e32 v61, v61
	v_add_f32_e32 v62, 1.0, v62
	v_add_f32_e32 v63, 1.0, v63
	v_rcp_f32_e32 v62, v62
	v_rcp_f32_e32 v63, v63
	v_pk_mul_f32 v[56:57], v[56:57], v[60:61]
	v_pk_mul_f32 v[48:49], v[48:49], v[70:71] op_sel_hi:[1,0]
	v_pk_mul_f32 v[50:51], v[50:51], v[70:71] op_sel_hi:[1,0]
	v_pk_mul_f32 v[56:57], v[48:49], v[56:57]
	v_pk_mul_f32 v[48:49], v[58:59], v[62:63]
	s_nop 0
	v_pk_mul_f32 v[58:59], v[50:51], v[48:49]
	v_cvt_pk_bf16_f32 v48, v52, v53
	v_fmamk_f32 v52, v178, 0x3a800000, v156
	v_mul_f32_e32 v53, 0x4b800000, v52
	v_cmp_gt_f32_e32 vcc, s39, v52
	v_cvt_pk_bf16_f32 v49, v54, v55
	v_cvt_pk_bf16_f32 v50, v56, v57
	v_cndmask_b32_e32 v52, v52, v53, vcc
	v_rsq_f32_e32 v54, v52
	v_mad_i64_i32 v[52:53], s[8:9], v174, s40, v[146:147]
	v_cvt_pk_bf16_f32 v51, v58, v59
	v_mul_f32_e32 v55, 0x45800000, v54
	v_cndmask_b32_e32 v54, v54, v55, vcc
	v_pk_mul_f32 v[44:45], v[44:45], v[54:55] op_sel_hi:[1,0]
	v_lshl_add_u64 v[52:53], v[52:53], 0, v[148:149]
	v_mul_f32_e32 v55, 0xbfb8aa3b, v44
	v_exp_f32_e32 v55, v55
	v_mul_f32_e32 v56, 0xbfb8aa3b, v45
	v_exp_f32_e32 v56, v56
	global_store_dwordx4 v[52:53], v[48:51], off nt
	v_pk_mul_f32 v[46:47], v[46:47], v[54:55] op_sel_hi:[1,0]
	v_pk_mul_f32 v[36:37], v[36:37], v[54:55] op_sel_hi:[1,0]
	v_mul_f32_e32 v50, 0xbfb8aa3b, v46
	v_mul_f32_e32 v51, 0xbfb8aa3b, v47
	v_exp_f32_e32 v50, v50
	v_exp_f32_e32 v51, v51
	v_add_f32_e32 v48, 1.0, v55
	v_add_f32_e32 v49, 1.0, v56
	v_rcp_f32_e32 v48, v48
	v_rcp_f32_e32 v49, v49
	v_add_f32_e32 v50, 1.0, v50
	v_add_f32_e32 v51, 1.0, v51
	v_rcp_f32_e32 v50, v50
	v_rcp_f32_e32 v51, v51
	v_pk_mul_f32 v[44:45], v[44:45], v[48:49]
	v_pk_mul_f32 v[40:41], v[40:41], v[54:55] op_sel_hi:[1,0]
	v_pk_mul_f32 v[36:37], v[36:37], v[44:45]
	v_pk_mul_f32 v[44:45], v[46:47], v[50:51]
	v_mul_f32_e32 v46, 0xbfb8aa3b, v40
	v_mul_f32_e32 v47, 0xbfb8aa3b, v41
	v_exp_f32_e32 v46, v46
	v_exp_f32_e32 v47, v47
	v_pk_mul_f32 v[38:39], v[38:39], v[54:55] op_sel_hi:[1,0]
	v_pk_mul_f32 v[42:43], v[42:43], v[54:55] op_sel_hi:[1,0]
	v_pk_mul_f32 v[38:39], v[38:39], v[44:45]
	v_add_f32_e32 v44, 1.0, v46
	v_add_f32_e32 v45, 1.0, v47
	v_mul_f32_e32 v46, 0xbfb8aa3b, v42
	v_mul_f32_e32 v47, 0xbfb8aa3b, v43
	v_exp_f32_e32 v46, v46
	v_exp_f32_e32 v47, v47
	v_rcp_f32_e32 v44, v44
	v_rcp_f32_e32 v45, v45
	v_add_f32_e32 v46, 1.0, v46
	v_add_f32_e32 v47, 1.0, v47
	v_rcp_f32_e32 v46, v46
	v_rcp_f32_e32 v47, v47
	v_pk_mul_f32 v[40:41], v[40:41], v[44:45]
	v_pk_mul_f32 v[32:33], v[32:33], v[54:55] op_sel_hi:[1,0]
	v_pk_mul_f32 v[34:35], v[34:35], v[54:55] op_sel_hi:[1,0]
	v_pk_mul_f32 v[40:41], v[32:33], v[40:41]
	v_pk_mul_f32 v[32:33], v[42:43], v[46:47]
	v_add_u32_e32 v44, 0x90, v144
	v_pk_mul_f32 v[42:43], v[34:35], v[32:33]
	v_cvt_pk_bf16_f32 v32, v36, v37
	v_fmamk_f32 v36, v157, 0x3a800000, v156
	v_mul_f32_e32 v37, 0x4b800000, v36
	v_cmp_gt_f32_e32 vcc, s39, v36
	v_cvt_pk_bf16_f32 v33, v38, v39
	v_cvt_pk_bf16_f32 v34, v40, v41
	v_cndmask_b32_e32 v36, v36, v37, vcc
	v_rsq_f32_e32 v38, v36
	v_mad_i64_i32 v[36:37], s[8:9], v44, s40, v[146:147]
	v_cvt_pk_bf16_f32 v35, v42, v43
	v_mul_f32_e32 v39, 0x45800000, v38
	v_cndmask_b32_e32 v38, v38, v39, vcc
	v_pk_mul_f32 v[28:29], v[28:29], v[38:39] op_sel_hi:[1,0]
	v_lshl_add_u64 v[36:37], v[36:37], 0, v[148:149]
	v_mul_f32_e32 v39, 0xbfb8aa3b, v28
	v_exp_f32_e32 v39, v39
	v_mul_f32_e32 v40, 0xbfb8aa3b, v29
	v_exp_f32_e32 v40, v40
; #define PG8_BAR __builtin_amdgcn_s_barrier()
; DI float sigmoidf_(float v) { return __builtin_amdgcn_rcpf(1.f + __builtin_amdgcn_exp2f(-v * 1.4426950408889634f)); }
; DI u32x4 pack8(f32x4 a, f32x4 b) { u32x4 w; w.x = cvtpk(a[0], a[1]); w.y = cvtpk(a[2], a[3]); w.z = cvtpk(b[0], b[1]); w.w = cvtpk(b[2], b[3]); return w; }
; template <class Epi, class Sched, bool ALIGN_EPI = false, bool SP2 = false>
; __device__ __forceinline__ void gemm_phase(PG8_LAS unsigned char* lds, const Gemm g, const Sched& S, const Epi& E) {
;     ...
;         if constexpr (ALIGN_EPI) { if (wr == 0) PG8_BAR; }
;         if constexpr (!Epi::AFTER_DRAIN) { E(acc, cur, wr, wc, fr, fq); S.done(cur); }
;         if (!has_next) break;
; #pragma unroll
;         for (int a = 0; a < 2; ++a)
; #pragma unroll
;             for (int b = 0; b < 2; ++b)
; #pragma unroll
;                 for (int m = 0; m < 4; ++m)
; #pragma unroll
;                     for (int n = 0; n < 2; ++n) acc[a][b][m][n] = (f32x4){0.f, 0.f, 0.f, 0.f};
;         cur = nxt; cA = nA; cB = nB; ++ui;
;         if constexpr (ALIGN_EPI) { if (wr == 1) PG8_BAR; }
;   DI void operator()(const f32x4 (&acc)[2][2][4][2], const Unit& u, int wr, int wc, int fr, int fq) const {
;     ...
;       for (int m = 0; m < 4; ++m) {
;         const int row = row0 + ai * 128 + m * 16;
;         const float rstd = rsqrtf(rs[ai * 4 + m] * (1.f / DM) + EPSN);
;         f32x4 o[2];
; #pragma unroll
;         for (int n = 0; n < 2; ++n) {
;           const f32x4 a = acc[ai][0][m][n] * rstd, b = acc[ai][1][m][n] * rstd;
; #pragma unroll
;           for (int e = 0; e < 4; ++e) o[n][e] = a[e] * sigmoidf_(a[e]) * b[e];
;         }
;         __builtin_nontemporal_store(pack8(o[0], o[1]), (u32x4*)(H + (size_t)row * DFF + hcol));
	global_store_dwordx4 v[36:37], v[32:35], off nt
	v_pk_mul_f32 v[30:31], v[30:31], v[38:39] op_sel_hi:[1,0]
	v_pk_mul_f32 v[20:21], v[20:21], v[38:39] op_sel_hi:[1,0]
	v_mul_f32_e32 v34, 0xbfb8aa3b, v30
	v_mul_f32_e32 v35, 0xbfb8aa3b, v31
	v_exp_f32_e32 v34, v34
	v_exp_f32_e32 v35, v35
	v_add_f32_e32 v32, 1.0, v39
	v_add_f32_e32 v33, 1.0, v40
	v_rcp_f32_e32 v32, v32
	v_rcp_f32_e32 v33, v33
	v_add_f32_e32 v34, 1.0, v34
	v_add_f32_e32 v35, 1.0, v35
	v_rcp_f32_e32 v34, v34
	v_rcp_f32_e32 v35, v35
	v_pk_mul_f32 v[28:29], v[28:29], v[32:33]
	v_pk_mul_f32 v[24:25], v[24:25], v[38:39] op_sel_hi:[1,0]
	v_pk_mul_f32 v[20:21], v[20:21], v[28:29]
	v_pk_mul_f32 v[28:29], v[30:31], v[34:35]
	v_mul_f32_e32 v30, 0xbfb8aa3b, v24
	v_mul_f32_e32 v31, 0xbfb8aa3b, v25
	v_exp_f32_e32 v30, v30
	v_exp_f32_e32 v31, v31
	v_pk_mul_f32 v[22:23], v[22:23], v[38:39] op_sel_hi:[1,0]
	v_pk_mul_f32 v[26:27], v[26:27], v[38:39] op_sel_hi:[1,0]
	v_pk_mul_f32 v[22:23], v[22:23], v[28:29]
	v_add_f32_e32 v28, 1.0, v30
	v_add_f32_e32 v29, 1.0, v31
	v_mul_f32_e32 v30, 0xbfb8aa3b, v26
	v_mul_f32_e32 v31, 0xbfb8aa3b, v27
	v_exp_f32_e32 v30, v30
	v_exp_f32_e32 v31, v31
	v_rcp_f32_e32 v28, v28
	v_rcp_f32_e32 v29, v29
	v_add_f32_e32 v30, 1.0, v30
	v_add_f32_e32 v31, 1.0, v31
	v_rcp_f32_e32 v30, v30
	v_rcp_f32_e32 v31, v31
	v_pk_mul_f32 v[24:25], v[24:25], v[28:29]
	v_pk_mul_f32 v[16:17], v[16:17], v[38:39] op_sel_hi:[1,0]
	v_pk_mul_f32 v[18:19], v[18:19], v[38:39] op_sel_hi:[1,0]
	v_pk_mul_f32 v[24:25], v[16:17], v[24:25]
	v_pk_mul_f32 v[16:17], v[26:27], v[30:31]
	v_add_u32_e32 v28, 0xa0, v144
	v_pk_mul_f32 v[26:27], v[18:19], v[16:17]
	v_cvt_pk_bf16_f32 v16, v20, v21
	v_fmamk_f32 v20, v145, 0x3a800000, v156
	v_mul_f32_e32 v21, 0x4b800000, v20
	v_cmp_gt_f32_e32 vcc, s39, v20
	v_cvt_pk_bf16_f32 v17, v22, v23
	v_cvt_pk_bf16_f32 v18, v24, v25
	v_cndmask_b32_e32 v20, v20, v21, vcc
	v_rsq_f32_e32 v22, v20
	v_mad_i64_i32 v[20:21], s[8:9], v28, s40, v[146:147]
	v_cvt_pk_bf16_f32 v19, v26, v27
	v_mul_f32_e32 v23, 0x45800000, v22
	v_cndmask_b32_e32 v22, v22, v23, vcc
	v_pk_mul_f32 v[12:13], v[12:13], v[22:23] op_sel_hi:[1,0]
	v_lshl_add_u64 v[20:21], v[20:21], 0, v[148:149]
	v_mul_f32_e32 v23, 0xbfb8aa3b, v12
	v_exp_f32_e32 v23, v23
	v_mul_f32_e32 v24, 0xbfb8aa3b, v13
	v_exp_f32_e32 v24, v24
	global_store_dwordx4 v[20:21], v[16:19], off nt
	v_pk_mul_f32 v[14:15], v[14:15], v[22:23] op_sel_hi:[1,0]
	v_pk_mul_f32 v[4:5], v[4:5], v[22:23] op_sel_hi:[1,0]
	v_mul_f32_e32 v18, 0xbfb8aa3b, v14
	v_mul_f32_e32 v19, 0xbfb8aa3b, v15
	v_exp_f32_e32 v18, v18
	v_exp_f32_e32 v19, v19
	v_add_f32_e32 v16, 1.0, v23
	v_add_f32_e32 v17, 1.0, v24
	v_rcp_f32_e32 v16, v16
	v_rcp_f32_e32 v17, v17
	v_add_f32_e32 v18, 1.0, v18
	v_add_f32_e32 v19, 1.0, v19
	v_rcp_f32_e32 v18, v18
	v_rcp_f32_e32 v19, v19
	v_pk_mul_f32 v[12:13], v[12:13], v[16:17]
	v_pk_mul_f32 v[8:9], v[8:9], v[22:23] op_sel_hi:[1,0]
	v_pk_mul_f32 v[4:5], v[4:5], v[12:13]
	v_pk_mul_f32 v[12:13], v[14:15], v[18:19]
	v_mul_f32_e32 v14, 0xbfb8aa3b, v8
	v_mul_f32_e32 v15, 0xbfb8aa3b, v9
	v_exp_f32_e32 v14, v14
	v_exp_f32_e32 v15, v15
	v_pk_mul_f32 v[6:7], v[6:7], v[22:23] op_sel_hi:[1,0]
	v_pk_mul_f32 v[10:11], v[10:11], v[22:23] op_sel_hi:[1,0]
	v_pk_mul_f32 v[6:7], v[6:7], v[12:13]
	v_add_f32_e32 v12, 1.0, v14
	v_add_f32_e32 v13, 1.0, v15
	v_mul_f32_e32 v14, 0xbfb8aa3b, v10
	v_mul_f32_e32 v15, 0xbfb8aa3b, v11
	v_exp_f32_e32 v14, v14
	v_exp_f32_e32 v15, v15
	v_rcp_f32_e32 v12, v12
	v_rcp_f32_e32 v13, v13
	v_add_f32_e32 v14, 1.0, v14
	v_add_f32_e32 v15, 1.0, v15
	v_rcp_f32_e32 v14, v14
	v_rcp_f32_e32 v15, v15
	v_pk_mul_f32 v[8:9], v[8:9], v[12:13]
	v_pk_mul_f32 v[0:1], v[0:1], v[22:23] op_sel_hi:[1,0]
	v_pk_mul_f32 v[2:3], v[2:3], v[22:23] op_sel_hi:[1,0]
	v_pk_mul_f32 v[8:9], v[0:1], v[8:9]
	v_pk_mul_f32 v[0:1], v[10:11], v[14:15]
	v_add_u32_e32 v12, 0xb0, v144
	v_pk_mul_f32 v[10:11], v[2:3], v[0:1]
	v_cvt_pk_bf16_f32 v0, v4, v5
	v_mad_i64_i32 v[4:5], s[8:9], v12, s40, v[146:147]
	v_cvt_pk_bf16_f32 v1, v6, v7
	v_cvt_pk_bf16_f32 v2, v8, v9
	v_cvt_pk_bf16_f32 v3, v10, v11
	v_lshl_add_u64 v[4:5], v[4:5], 0, v[148:149]
	s_andn2_b64 vcc, exec, s[6:7]
	s_mov_b64 s[6:7], -1
	global_store_dwordx4 v[4:5], v[0:3], off nt
	s_cbranch_vccnz .LBB0_448
	s_andn2_b64 vcc, exec, s[0:1]
	s_cbranch_vccnz .LBB0_447
	s_barrier
	s_branch .LBB0_447

; #define PG8_STAGE(bufoff, gbase, voff) do { _Pragma("unroll") for (int _i = 0; _i < 2; ++_i) \
;         __builtin_amdgcn_global_load_lds((const unsigned*)((const char*)(gbase) + (voff)[_i]), (PG8_LAS unsigned*)(lds + (bufoff) + ldsw + _i * 8192), 16, 0, 0); } while (0)
; #define PG8_WAIT_V(n) asm volatile("s_waitcnt vmcnt(" #n ")" ::: "memory")
; #define PG8_BAR __builtin_amdgcn_s_barrier()
; template <class Epi, class Sched, bool ALIGN_EPI = false, bool SP2 = false>
; __device__ __forceinline__ void gemm_phase(PG8_LAS unsigned char* lds, const Gemm g, const Sched& S, const Epi& E) {
;     ...
;     for (int i = 0; i < 2; ++i) { int R, C; stage_rc(tid * 16 + i * 8192, R, C); const int Rb = Epi::PERM ? ((R & ~31) + perm32(R & 31)) : R;
;         voffA[i] = (unsigned)(R * K + C) * 2u; voffB[i] = (unsigned)(Rb * K + C) * 2u; }
;     const size_t kstep = (size_t)(BK * 2);
;     const size_t hstep = (size_t)HALF * K * 2;
;     const size_t tstep = 2 * hstep;
;     const unsigned ldsw = (unsigned)wid * 1024u;
;     const int aoff = lds_byte(wr * 64 + fr, fq * 8), boff = lds_byte(wc * 32 + fr, fq * 8);
;     ...
;         PG8_WAIT_V(2); PG8_BAR;
;         PG8_STAGE(PG8_SB(1, 0), cB + kstep, voffB); PG8_STAGE(PG8_SA(1, 0), cA + kstep, voffA); PG8_STAGE(PG8_SB(1, 1), cB + hstep + kstep, voffB);
;         PG8_WAIT_V(6); PG8_BAR;
.LBB0_1247:
	s_lshl_b32 s4, s4, 5
	s_and_b32 s14, s4, 0x60
	s_mov_b64 s[4:5], 0x80
	s_add_i32 m0, s28, 0x18000
	v_lshl_add_u64 v[6:7], v[6:7], 0, s[4:5]
	s_lshl_b32 s9, s8, 13
	s_lshl_b32 s15, s14, 7
	s_waitcnt vmcnt(2)
	s_barrier
	global_load_lds_dwordx4 v[6:7], off
	v_lshl_add_u64 v[4:5], v[4:5], 0, s[4:5]
	s_add_i32 m0, s28, 0x1a000
	s_add_i32 s34, s28, 0x8000
	s_add_i32 s35, s28, 0xa000
	global_load_lds_dwordx4 v[4:5], off
	v_lshl_add_u64 v[0:1], v[0:1], 0, s[4:5]
	s_mov_b32 m0, s34
	s_add_u32 s12, s22, 0x40080
	global_load_lds_dwordx4 v[0:1], off
	v_lshl_add_u64 v[0:1], v[2:3], 0, s[4:5]
	s_mov_b32 m0, s35
	s_addc_u32 s13, s23, 0
	global_load_lds_dwordx4 v[0:1], off
	s_add_i32 m0, s28, 0x1c000
	v_lshl_add_u64 v[0:1], s[12:13], 0, v[132:133]
	global_load_lds_dwordx4 v[0:1], off
	v_lshl_add_u64 v[0:1], s[12:13], 0, v[128:129]
	s_add_i32 m0, s28, 0x1e000
	s_cmpk_lt_u32 s7, 0x100
	global_load_lds_dwordx4 v[0:1], off
	v_lshrrev_b32_e32 v1, 1, v8
	v_and_b32_e32 v1, 24, v1
	v_and_b32_e32 v0, 15, v8
	v_lshlrev_b32_e32 v2, 1, v1
	v_lshl_or_b32 v150, s8, 6, v0
	v_lshl_or_b32 v0, v0, 6, v2
	v_lshlrev_b32_e32 v2, 2, v8
	v_and_b32_e32 v2, 32, v2
	v_bitop3_b32 v3, v0, s9, v2 bitop3:0xde
	v_bitop3_b32 v151, v0, s15, v2 bitop3:0xde
	v_lshlrev_b32_e32 v0, 14, v13
	v_and_b32_e32 v0, 0xffff8000, v0
	v_or_b32_e32 v152, s14, v1
	v_lshl_add_u32 v0, v12, 11, v0
	v_and_b32_e32 v1, 1, v13
	v_lshl_or_b32 v0, v1, 6, v0
	v_lshl_add_u32 v136, v14, 1, v0
	v_lshlrev_b32_e32 v0, 14, v9
	v_and_b32_e32 v0, 0xffff8000, v0
	s_waitcnt vmcnt(6)
	v_lshl_add_u32 v0, v10, 11, v0
	v_and_b32_e32 v1, 1, v9
	s_sext_i32_i16 s11, s6
	s_cselect_b64 s[6:7], -1, 0
	v_lshl_or_b32 v0, v1, 6, v0
	s_add_i32 s36, 0, 0x10000
	s_add_i32 s37, 0, 0x14000
	v_mov_b32_e32 v137, v133
	v_lshl_add_u32 v138, v11, 1, v0
	v_mov_b32_e32 v139, v133
	v_mov_b64_e32 v[140:141], 0x1600
	v_mov_b64_e32 v[142:143], 0x15ff
	v_add_u32_e32 v153, s36, v151
	v_add_u32_e32 v154, s37, v151
	v_add_u32_e32 v155, 0, v3
	v_mov_b32_e32 v156, 0x358637bd
	s_mov_b32 s38, 0x800000
	s_movk_i32 s39, 0x1600
	s_barrier
	v_lshl_add_u32 v244, s10, 8, v150
	v_ashrrev_i32_e32 v245, 31, v244
	v_lshl_add_u64 v[244:245], v[244:245], 2, s[66:67]
	global_load_dword v236, v[244:245], off
	global_load_dword v237, v[244:245], off offset:64
	global_load_dword v238, v[244:245], off offset:128
	global_load_dword v239, v[244:245], off offset:192
	global_load_dword v240, v[244:245], off offset:512
	global_load_dword v241, v[244:245], off offset:576
	global_load_dword v242, v[244:245], off offset:640
	global_load_dword v243, v[244:245], off offset:704
	s_branch .LBB0_1250

; DI float sigmoidf_(float v) { return __builtin_amdgcn_rcpf(1.f + __builtin_amdgcn_exp2f(-v * 1.4426950408889634f)); }
; DI u32x4 pack8(f32x4 a, f32x4 b) { u32x4 w; w.x = cvtpk(a[0], a[1]); w.y = cvtpk(a[2], a[3]); w.z = cvtpk(b[0], b[1]); w.w = cvtpk(b[2], b[3]); return w; }
;   DI void operator()(const f32x4 (&acc)[2][2][4][2], const Unit& u, int wr, int wc, int fr, int fq) const {
;     const int row0 = u.pm * 256 + wr * 64 + fr; const int hcol = u.pn * 128 + wc * 32 + 8 * fq;
;     float rs[8];
; #pragma unroll
;     for (int i = 0; i < 8; ++i) rs[i] = ssq[row0 + (i >> 2) * 128 + (i & 3) * 16];
; #pragma unroll
;     for (int ai = 0; ai < 2; ++ai)
; #pragma unroll
;       for (int m = 0; m < 4; ++m) {
;         const int row = row0 + ai * 128 + m * 16;
;         const float rstd = rsqrtf(rs[ai * 4 + m] * (1.f / DM) + EPSN);
;         f32x4 o[2];
; #pragma unroll
;         for (int n = 0; n < 2; ++n) {
;           const f32x4 a = acc[ai][0][m][n] * rstd, b = acc[ai][1][m][n] * rstd;
; #pragma unroll
;           for (int e = 0; e < 4; ++e) o[n][e] = a[e] * sigmoidf_(a[e]) * b[e];
;         }
;         __builtin_nontemporal_store(pack8(o[0], o[1]), (u32x4*)(H + (size_t)row * DFF + hcol));
.LBB0_1256:
	v_lshl_add_u32 v144, s10, 8, v150
	v_ashrrev_i32_e32 v145, 31, v144
	v_lshl_add_u64 v[148:149], v[144:145], 2, s[66:67]
	v_mov_b32_e32 v162, v236
	v_mov_b32_e32 v163, v237
	v_mov_b32_e32 v175, v238
	v_mov_b32_e32 v176, v239
	v_mov_b32_e32 v177, v240
	v_mov_b32_e32 v178, v241
	v_mov_b32_e32 v157, v242
	v_mov_b32_e32 v145, v243
	s_and_b32 vcc_lo, s14, 0xff
	v_lshl_add_u32 v244, vcc_lo, 8, v150
	v_ashrrev_i32_e32 v245, 31, v244
	v_lshl_add_u64 v[244:245], v[244:245], 2, s[66:67]
	global_load_dword v236, v[244:245], off
	global_load_dword v237, v[244:245], off offset:64
	global_load_dword v238, v[244:245], off offset:128
	global_load_dword v239, v[244:245], off offset:192
	global_load_dword v240, v[244:245], off offset:512
	global_load_dword v241, v[244:245], off offset:576
	global_load_dword v242, v[244:245], off offset:640
	global_load_dword v243, v[244:245], off offset:704
	v_lshl_or_b32 v158, s11, 7, v152
	v_readlane_b32 s10, v252, 3
	v_readlane_b32 s11, v252, 4
	v_ashrrev_i32_e32 v159, 31, v158
	v_add_u32_e32 v174, 0x80, v144
	v_mov_b64_e32 v[146:147], s[10:11]
	v_mad_i64_i32 v[160:161], s[10:11], v144, s39, v[146:147]
	v_fmamk_f32 v148, v162, 0x3a800000, v156
	v_fmamk_f32 v149, v163, 0x3a800000, v156
	v_mul_f32_e32 v162, 0x4b800000, v148
	v_cmp_gt_f32_e32 vcc, s38, v148
	v_mul_f32_e32 v163, 0x4b800000, v149
	v_cmp_gt_f32_e64 s[10:11], s38, v149
	v_cndmask_b32_e32 v148, v148, v162, vcc
	v_rsq_f32_e32 v162, v148
	v_cndmask_b32_e64 v149, v149, v163, s[10:11]
	v_rsq_f32_e32 v163, v149
	v_lshlrev_b64 v[148:149], 1, v[158:159]
	v_lshl_add_u64 v[158:159], v[160:161], 0, v[148:149]
	v_mul_f32_e32 v160, 0x45800000, v162
	v_mul_f32_e32 v161, 0x45800000, v163
	v_cndmask_b32_e32 v160, v162, v160, vcc
	v_cndmask_b32_e64 v162, v163, v161, s[10:11]
	v_pk_mul_f32 v[124:125], v[124:125], v[160:161] op_sel_hi:[1,0]
	v_pk_mul_f32 v[126:127], v[126:127], v[160:161] op_sel_hi:[1,0]
	v_pk_mul_f32 v[120:121], v[120:121], v[160:161] op_sel_hi:[1,0]
	v_pk_mul_f32 v[122:123], v[122:123], v[160:161] op_sel_hi:[1,0]
	v_pk_mul_f32 v[112:113], v[112:113], v[160:161] op_sel_hi:[1,0]
	v_pk_mul_f32 v[114:115], v[114:115], v[160:161] op_sel_hi:[1,0]
	v_pk_mul_f32 v[108:109], v[108:109], v[160:161] op_sel_hi:[1,0]
	v_pk_mul_f32 v[110:111], v[110:111], v[160:161] op_sel_hi:[1,0]
	v_pk_mul_f32 v[116:117], v[116:117], v[162:163] op_sel_hi:[1,0]
	v_pk_mul_f32 v[100:101], v[100:101], v[162:163] op_sel_hi:[1,0]
	v_pk_mul_f32 v[118:119], v[118:119], v[162:163] op_sel_hi:[1,0]
	v_mul_f32_e32 v160, 0xbfb8aa3b, v124
	v_mul_f32_e32 v161, 0xbfb8aa3b, v125
	v_mul_f32_e32 v163, 0xbfb8aa3b, v126
	v_mul_f32_e32 v164, 0xbfb8aa3b, v127
	v_mul_f32_e32 v165, 0xbfb8aa3b, v120
	v_mul_f32_e32 v166, 0xbfb8aa3b, v121
	v_mul_f32_e32 v167, 0xbfb8aa3b, v122
	v_mul_f32_e32 v168, 0xbfb8aa3b, v123
	v_mul_f32_e32 v169, 0xbfb8aa3b, v116
	v_exp_f32_e32 v160, v160
	v_exp_f32_e32 v161, v161
	v_exp_f32_e32 v163, v163
	v_exp_f32_e32 v164, v164
	v_exp_f32_e32 v165, v165
	v_exp_f32_e32 v166, v166
	v_exp_f32_e32 v167, v167
	v_exp_f32_e32 v168, v168
	v_exp_f32_e32 v169, v169
	v_add_f32_e32 v160, 1.0, v160
	v_add_f32_e32 v161, 1.0, v161
	v_add_f32_e32 v163, 1.0, v163
	v_add_f32_e32 v173, 1.0, v164
	v_add_f32_e32 v179, 1.0, v165
	v_add_f32_e32 v180, 1.0, v166
	v_add_f32_e32 v181, 1.0, v167
	v_add_f32_e32 v182, 1.0, v168
	v_add_f32_e32 v183, 1.0, v169
	v_rcp_f32_e32 v160, v160
	v_rcp_f32_e32 v161, v161
	v_rcp_f32_e32 v164, v163
	v_rcp_f32_e32 v165, v173
	v_rcp_f32_e32 v166, v179
	v_rcp_f32_e32 v167, v180
	v_rcp_f32_e32 v168, v181
	v_rcp_f32_e32 v169, v182
	v_mul_f32_e32 v171, 0xbfb8aa3b, v118
	v_mul_f32_e32 v172, 0xbfb8aa3b, v119
	v_exp_f32_e32 v171, v171
	v_exp_f32_e32 v172, v172
	v_pk_mul_f32 v[124:125], v[124:125], v[160:161]
	v_pk_mul_f32 v[126:127], v[126:127], v[164:165]
	v_pk_mul_f32 v[120:121], v[120:121], v[166:167]
	v_pk_mul_f32 v[122:123], v[122:123], v[168:169]
	v_pk_mul_f32 v[112:113], v[112:113], v[124:125]
	v_pk_mul_f32 v[114:115], v[114:115], v[126:127]
	v_pk_mul_f32 v[120:121], v[108:109], v[120:121]
	v_pk_mul_f32 v[122:123], v[110:111], v[122:123]
	v_add_f32_e32 v185, 1.0, v171
	v_add_f32_e32 v186, 1.0, v172
	v_cvt_pk_bf16_f32 v108, v112, v113
	v_cvt_pk_bf16_f32 v109, v114, v115
	v_cvt_pk_bf16_f32 v110, v120, v121
	v_cvt_pk_bf16_f32 v111, v122, v123
	v_pk_mul_f32 v[104:105], v[104:105], v[162:163] op_sel_hi:[1,0]
	v_rcp_f32_e32 v172, v185
	v_rcp_f32_e32 v173, v186
	global_store_dwordx4 v[158:159], v[108:111], off nt
	v_mul_f32_e32 v170, 0xbfb8aa3b, v117
	v_pk_mul_f32 v[102:103], v[102:103], v[162:163] op_sel_hi:[1,0]
	v_mul_f32_e32 v110, 0xbfb8aa3b, v104
	v_mul_f32_e32 v111, 0xbfb8aa3b, v105
	v_exp_f32_e32 v110, v110
	v_exp_f32_e32 v111, v111
	v_pk_mul_f32 v[108:109], v[118:119], v[172:173]
	v_pk_mul_f32 v[106:107], v[106:107], v[162:163] op_sel_hi:[1,0]
	v_exp_f32_e32 v170, v170
	v_pk_mul_f32 v[102:103], v[102:103], v[108:109]
	v_add_f32_e32 v108, 1.0, v110
	v_add_f32_e32 v109, 1.0, v111
	v_mul_f32_e32 v110, 0xbfb8aa3b, v106
	v_mul_f32_e32 v111, 0xbfb8aa3b, v107
	v_exp_f32_e32 v110, v110
	v_exp_f32_e32 v111, v111
	v_add_f32_e32 v184, 1.0, v170
	v_rcp_f32_e32 v170, v183
	v_rcp_f32_e32 v171, v184
	v_rcp_f32_e32 v108, v108
	v_rcp_f32_e32 v109, v109
	v_add_f32_e32 v110, 1.0, v110
	v_add_f32_e32 v111, 1.0, v111
	v_rcp_f32_e32 v110, v110
	v_rcp_f32_e32 v111, v111
	v_pk_mul_f32 v[116:117], v[116:117], v[170:171]
	v_pk_mul_f32 v[104:105], v[104:105], v[108:109]
	v_pk_mul_f32 v[96:97], v[96:97], v[162:163] op_sel_hi:[1,0]
	v_pk_mul_f32 v[100:101], v[100:101], v[116:117]
	v_pk_mul_f32 v[104:105], v[96:97], v[104:105]
	v_pk_mul_f32 v[96:97], v[106:107], v[110:111]
; DI float sigmoidf_(float v) { return __builtin_amdgcn_rcpf(1.f + __builtin_amdgcn_exp2f(-v * 1.4426950408889634f)); }
; DI u32x4 pack8(f32x4 a, f32x4 b) { u32x4 w; w.x = cvtpk(a[0], a[1]); w.y = cvtpk(a[2], a[3]); w.z = cvtpk(b[0], b[1]); w.w = cvtpk(b[2], b[3]); return w; }
;   DI void operator()(const f32x4 (&acc)[2][2][4][2], const Unit& u, int wr, int wc, int fr, int fq) const {
;     ...
;       for (int m = 0; m < 4; ++m) {
;         const int row = row0 + ai * 128 + m * 16;
;         const float rstd = rsqrtf(rs[ai * 4 + m] * (1.f / DM) + EPSN);
;         f32x4 o[2];
; #pragma unroll
;         for (int n = 0; n < 2; ++n) {
;           const f32x4 a = acc[ai][0][m][n] * rstd, b = acc[ai][1][m][n] * rstd;
; #pragma unroll
;           for (int e = 0; e < 4; ++e) o[n][e] = a[e] * sigmoidf_(a[e]) * b[e];
;         }
;         __builtin_nontemporal_store(pack8(o[0], o[1]), (u32x4*)(H + (size_t)row * DFF + hcol));
	v_pk_mul_f32 v[98:99], v[98:99], v[162:163] op_sel_hi:[1,0]
	v_or_b32_e32 v108, 16, v144
	v_pk_mul_f32 v[106:107], v[98:99], v[96:97]
	v_cvt_pk_bf16_f32 v96, v100, v101
	v_fmamk_f32 v100, v175, 0x3a800000, v156
	v_mul_f32_e32 v101, 0x4b800000, v100
	v_cmp_gt_f32_e32 vcc, s38, v100
	v_cvt_pk_bf16_f32 v97, v102, v103
	v_cvt_pk_bf16_f32 v98, v104, v105
	v_cndmask_b32_e32 v100, v100, v101, vcc
	v_rsq_f32_e32 v102, v100
	v_mad_i64_i32 v[100:101], s[10:11], v108, s39, v[146:147]
	v_cvt_pk_bf16_f32 v99, v106, v107
	v_mul_f32_e32 v103, 0x45800000, v102
	v_cndmask_b32_e32 v102, v102, v103, vcc
	v_pk_mul_f32 v[92:93], v[92:93], v[102:103] op_sel_hi:[1,0]
	v_lshl_add_u64 v[100:101], v[100:101], 0, v[148:149]
	v_mul_f32_e32 v103, 0xbfb8aa3b, v92
	v_exp_f32_e32 v103, v103
	v_mul_f32_e32 v104, 0xbfb8aa3b, v93
	v_exp_f32_e32 v104, v104
	global_store_dwordx4 v[100:101], v[96:99], off nt
	v_pk_mul_f32 v[94:95], v[94:95], v[102:103] op_sel_hi:[1,0]
	v_pk_mul_f32 v[84:85], v[84:85], v[102:103] op_sel_hi:[1,0]
	v_mul_f32_e32 v98, 0xbfb8aa3b, v94
	v_mul_f32_e32 v99, 0xbfb8aa3b, v95
	v_exp_f32_e32 v98, v98
	v_exp_f32_e32 v99, v99
	v_add_f32_e32 v96, 1.0, v103
	v_add_f32_e32 v97, 1.0, v104
	v_rcp_f32_e32 v96, v96
	v_rcp_f32_e32 v97, v97
	v_add_f32_e32 v98, 1.0, v98
	v_add_f32_e32 v99, 1.0, v99
	v_rcp_f32_e32 v98, v98
	v_rcp_f32_e32 v99, v99
	v_pk_mul_f32 v[92:93], v[92:93], v[96:97]
	v_pk_mul_f32 v[88:89], v[88:89], v[102:103] op_sel_hi:[1,0]
	v_pk_mul_f32 v[84:85], v[84:85], v[92:93]
	v_pk_mul_f32 v[92:93], v[94:95], v[98:99]
	v_mul_f32_e32 v94, 0xbfb8aa3b, v88
	v_mul_f32_e32 v95, 0xbfb8aa3b, v89
	v_exp_f32_e32 v94, v94
	v_exp_f32_e32 v95, v95
	v_pk_mul_f32 v[86:87], v[86:87], v[102:103] op_sel_hi:[1,0]
	v_pk_mul_f32 v[90:91], v[90:91], v[102:103] op_sel_hi:[1,0]
	v_pk_mul_f32 v[86:87], v[86:87], v[92:93]
	v_add_f32_e32 v92, 1.0, v94
	v_add_f32_e32 v93, 1.0, v95
	v_mul_f32_e32 v94, 0xbfb8aa3b, v90
	v_mul_f32_e32 v95, 0xbfb8aa3b, v91
	v_exp_f32_e32 v94, v94
	v_exp_f32_e32 v95, v95
	v_rcp_f32_e32 v92, v92
	v_rcp_f32_e32 v93, v93
	v_add_f32_e32 v94, 1.0, v94
	v_add_f32_e32 v95, 1.0, v95
	v_rcp_f32_e32 v94, v94
	v_rcp_f32_e32 v95, v95
	v_pk_mul_f32 v[88:89], v[88:89], v[92:93]
	v_pk_mul_f32 v[80:81], v[80:81], v[102:103] op_sel_hi:[1,0]
	v_pk_mul_f32 v[82:83], v[82:83], v[102:103] op_sel_hi:[1,0]
	v_pk_mul_f32 v[88:89], v[80:81], v[88:89]
	v_pk_mul_f32 v[80:81], v[90:91], v[94:95]
	v_or_b32_e32 v92, 32, v144
	v_pk_mul_f32 v[90:91], v[82:83], v[80:81]
	v_cvt_pk_bf16_f32 v80, v84, v85
	v_fmamk_f32 v84, v176, 0x3a800000, v156
	v_mul_f32_e32 v85, 0x4b800000, v84
	v_cmp_gt_f32_e32 vcc, s38, v84
	v_cvt_pk_bf16_f32 v81, v86, v87
	v_cvt_pk_bf16_f32 v82, v88, v89
	v_cndmask_b32_e32 v84, v84, v85, vcc
	v_rsq_f32_e32 v86, v84
	v_mad_i64_i32 v[84:85], s[10:11], v92, s39, v[146:147]
	v_cvt_pk_bf16_f32 v83, v90, v91
	v_mul_f32_e32 v87, 0x45800000, v86
	v_cndmask_b32_e32 v86, v86, v87, vcc
	v_pk_mul_f32 v[76:77], v[76:77], v[86:87] op_sel_hi:[1,0]
	v_lshl_add_u64 v[84:85], v[84:85], 0, v[148:149]
	v_mul_f32_e32 v87, 0xbfb8aa3b, v76
	v_exp_f32_e32 v87, v87
	v_mul_f32_e32 v88, 0xbfb8aa3b, v77
	v_exp_f32_e32 v88, v88
	global_store_dwordx4 v[84:85], v[80:83], off nt
	v_pk_mul_f32 v[78:79], v[78:79], v[86:87] op_sel_hi:[1,0]
	v_pk_mul_f32 v[68:69], v[68:69], v[86:87] op_sel_hi:[1,0]
	v_mul_f32_e32 v82, 0xbfb8aa3b, v78
	v_mul_f32_e32 v83, 0xbfb8aa3b, v79
	v_exp_f32_e32 v82, v82
	v_exp_f32_e32 v83, v83
	v_add_f32_e32 v80, 1.0, v87
	v_add_f32_e32 v81, 1.0, v88
	v_rcp_f32_e32 v80, v80
	v_rcp_f32_e32 v81, v81
	v_add_f32_e32 v82, 1.0, v82
	v_add_f32_e32 v83, 1.0, v83
	v_rcp_f32_e32 v82, v82
	v_rcp_f32_e32 v83, v83
	v_pk_mul_f32 v[76:77], v[76:77], v[80:81]
	v_pk_mul_f32 v[72:73], v[72:73], v[86:87] op_sel_hi:[1,0]
	v_pk_mul_f32 v[68:69], v[68:69], v[76:77]
	v_pk_mul_f32 v[76:77], v[78:79], v[82:83]
	v_mul_f32_e32 v78, 0xbfb8aa3b, v72
	v_mul_f32_e32 v79, 0xbfb8aa3b, v73
	v_exp_f32_e32 v78, v78
	v_exp_f32_e32 v79, v79
	v_pk_mul_f32 v[70:71], v[70:71], v[86:87] op_sel_hi:[1,0]
	v_pk_mul_f32 v[74:75], v[74:75], v[86:87] op_sel_hi:[1,0]
	v_pk_mul_f32 v[70:71], v[70:71], v[76:77]
	v_add_f32_e32 v76, 1.0, v78
	v_add_f32_e32 v77, 1.0, v79
	v_mul_f32_e32 v78, 0xbfb8aa3b, v74
	v_mul_f32_e32 v79, 0xbfb8aa3b, v75
	v_exp_f32_e32 v78, v78
	v_exp_f32_e32 v79, v79
	v_rcp_f32_e32 v76, v76
	v_rcp_f32_e32 v77, v77
	v_add_f32_e32 v78, 1.0, v78
	v_add_f32_e32 v79, 1.0, v79
	v_rcp_f32_e32 v78, v78
	v_rcp_f32_e32 v79, v79
	v_pk_mul_f32 v[72:73], v[72:73], v[76:77]
	v_pk_mul_f32 v[64:65], v[64:65], v[86:87] op_sel_hi:[1,0]
	v_pk_mul_f32 v[66:67], v[66:67], v[86:87] op_sel_hi:[1,0]
	v_pk_mul_f32 v[72:73], v[64:65], v[72:73]
	v_pk_mul_f32 v[64:65], v[74:75], v[78:79]
	v_or_b32_e32 v76, 48, v144
	v_pk_mul_f32 v[74:75], v[66:67], v[64:65]
	v_cvt_pk_bf16_f32 v64, v68, v69
	v_fmamk_f32 v68, v177, 0x3a800000, v156
	v_mul_f32_e32 v69, 0x4b800000, v68
	v_cmp_gt_f32_e32 vcc, s38, v68
	v_cvt_pk_bf16_f32 v65, v70, v71
	v_cvt_pk_bf16_f32 v66, v72, v73
	v_cndmask_b32_e32 v68, v68, v69, vcc
	v_rsq_f32_e32 v70, v68
	v_mad_i64_i32 v[68:69], s[10:11], v76, s39, v[146:147]
	v_cvt_pk_bf16_f32 v67, v74, v75
	v_mul_f32_e32 v71, 0x45800000, v70
	v_cndmask_b32_e32 v70, v70, v71, vcc
	v_pk_mul_f32 v[60:61], v[60:61], v[70:71] op_sel_hi:[1,0]
	v_lshl_add_u64 v[68:69], v[68:69], 0, v[148:149]
	v_mul_f32_e32 v71, 0xbfb8aa3b, v60
	v_exp_f32_e32 v71, v71
	v_mul_f32_e32 v72, 0xbfb8aa3b, v61
	v_exp_f32_e32 v72, v72
	global_store_dwordx4 v[68:69], v[64:67], off nt
	v_pk_mul_f32 v[62:63], v[62:63], v[70:71] op_sel_hi:[1,0]
	v_pk_mul_f32 v[52:53], v[52:53], v[70:71] op_sel_hi:[1,0]
	v_mul_f32_e32 v66, 0xbfb8aa3b, v62
	v_mul_f32_e32 v67, 0xbfb8aa3b, v63
; DI float sigmoidf_(float v) { return __builtin_amdgcn_rcpf(1.f + __builtin_amdgcn_exp2f(-v * 1.4426950408889634f)); }
; DI u32x4 pack8(f32x4 a, f32x4 b) { u32x4 w; w.x = cvtpk(a[0], a[1]); w.y = cvtpk(a[2], a[3]); w.z = cvtpk(b[0], b[1]); w.w = cvtpk(b[2], b[3]); return w; }
;   DI void operator()(const f32x4 (&acc)[2][2][4][2], const Unit& u, int wr, int wc, int fr, int fq) const {
;     ...
;       for (int m = 0; m < 4; ++m) {
;         const int row = row0 + ai * 128 + m * 16;
;         const float rstd = rsqrtf(rs[ai * 4 + m] * (1.f / DM) + EPSN);
;         f32x4 o[2];
; #pragma unroll
;         for (int n = 0; n < 2; ++n) {
;           const f32x4 a = acc[ai][0][m][n] * rstd, b = acc[ai][1][m][n] * rstd;
; #pragma unroll
;           for (int e = 0; e < 4; ++e) o[n][e] = a[e] * sigmoidf_(a[e]) * b[e];
;         }
;         __builtin_nontemporal_store(pack8(o[0], o[1]), (u32x4*)(H + (size_t)row * DFF + hcol));
	v_exp_f32_e32 v66, v66
	v_exp_f32_e32 v67, v67
	v_add_f32_e32 v64, 1.0, v71
	v_add_f32_e32 v65, 1.0, v72
	v_rcp_f32_e32 v64, v64
	v_rcp_f32_e32 v65, v65
	v_add_f32_e32 v66, 1.0, v66
	v_add_f32_e32 v67, 1.0, v67
	v_rcp_f32_e32 v66, v66
	v_rcp_f32_e32 v67, v67
	v_pk_mul_f32 v[60:61], v[60:61], v[64:65]
	v_pk_mul_f32 v[56:57], v[56:57], v[70:71] op_sel_hi:[1,0]
	v_pk_mul_f32 v[52:53], v[52:53], v[60:61]
	v_pk_mul_f32 v[60:61], v[62:63], v[66:67]
	v_mul_f32_e32 v62, 0xbfb8aa3b, v56
	v_mul_f32_e32 v63, 0xbfb8aa3b, v57
	v_exp_f32_e32 v62, v62
	v_exp_f32_e32 v63, v63
	v_pk_mul_f32 v[54:55], v[54:55], v[70:71] op_sel_hi:[1,0]
	v_pk_mul_f32 v[58:59], v[58:59], v[70:71] op_sel_hi:[1,0]
	v_pk_mul_f32 v[54:55], v[54:55], v[60:61]
	v_add_f32_e32 v60, 1.0, v62
	v_add_f32_e32 v61, 1.0, v63
	v_mul_f32_e32 v62, 0xbfb8aa3b, v58
	v_mul_f32_e32 v63, 0xbfb8aa3b, v59
	v_exp_f32_e32 v62, v62
	v_exp_f32_e32 v63, v63
	v_rcp_f32_e32 v60, v60
	v_rcp_f32_e32 v61, v61
	v_add_f32_e32 v62, 1.0, v62
	v_add_f32_e32 v63, 1.0, v63
	v_rcp_f32_e32 v62, v62
	v_rcp_f32_e32 v63, v63
	v_pk_mul_f32 v[56:57], v[56:57], v[60:61]
	v_pk_mul_f32 v[48:49], v[48:49], v[70:71] op_sel_hi:[1,0]
	v_pk_mul_f32 v[50:51], v[50:51], v[70:71] op_sel_hi:[1,0]
	v_pk_mul_f32 v[56:57], v[48:49], v[56:57]
	v_pk_mul_f32 v[48:49], v[58:59], v[62:63]
	s_nop 0
	v_pk_mul_f32 v[58:59], v[50:51], v[48:49]
	v_cvt_pk_bf16_f32 v48, v52, v53
	v_fmamk_f32 v52, v178, 0x3a800000, v156
	v_mul_f32_e32 v53, 0x4b800000, v52
	v_cmp_gt_f32_e32 vcc, s38, v52
	v_cvt_pk_bf16_f32 v49, v54, v55
	v_cvt_pk_bf16_f32 v50, v56, v57
	v_cndmask_b32_e32 v52, v52, v53, vcc
	v_rsq_f32_e32 v54, v52
	v_mad_i64_i32 v[52:53], s[10:11], v174, s39, v[146:147]
	v_cvt_pk_bf16_f32 v51, v58, v59
	v_mul_f32_e32 v55, 0x45800000, v54
	v_cndmask_b32_e32 v54, v54, v55, vcc
	v_pk_mul_f32 v[44:45], v[44:45], v[54:55] op_sel_hi:[1,0]
	v_lshl_add_u64 v[52:53], v[52:53], 0, v[148:149]
	v_mul_f32_e32 v55, 0xbfb8aa3b, v44
	v_exp_f32_e32 v55, v55
	v_mul_f32_e32 v56, 0xbfb8aa3b, v45
	v_exp_f32_e32 v56, v56
	global_store_dwordx4 v[52:53], v[48:51], off nt
	v_pk_mul_f32 v[46:47], v[46:47], v[54:55] op_sel_hi:[1,0]
	v_pk_mul_f32 v[36:37], v[36:37], v[54:55] op_sel_hi:[1,0]
	v_mul_f32_e32 v50, 0xbfb8aa3b, v46
	v_mul_f32_e32 v51, 0xbfb8aa3b, v47
	v_exp_f32_e32 v50, v50
	v_exp_f32_e32 v51, v51
	v_add_f32_e32 v48, 1.0, v55
	v_add_f32_e32 v49, 1.0, v56
	v_rcp_f32_e32 v48, v48
	v_rcp_f32_e32 v49, v49
	v_add_f32_e32 v50, 1.0, v50
	v_add_f32_e32 v51, 1.0, v51
	v_rcp_f32_e32 v50, v50
	v_rcp_f32_e32 v51, v51
	v_pk_mul_f32 v[44:45], v[44:45], v[48:49]
	v_pk_mul_f32 v[40:41], v[40:41], v[54:55] op_sel_hi:[1,0]
	v_pk_mul_f32 v[36:37], v[36:37], v[44:45]
	v_pk_mul_f32 v[44:45], v[46:47], v[50:51]
	v_mul_f32_e32 v46, 0xbfb8aa3b, v40
	v_mul_f32_e32 v47, 0xbfb8aa3b, v41
	v_exp_f32_e32 v46, v46
	v_exp_f32_e32 v47, v47
	v_pk_mul_f32 v[38:39], v[38:39], v[54:55] op_sel_hi:[1,0]
	v_pk_mul_f32 v[42:43], v[42:43], v[54:55] op_sel_hi:[1,0]
	v_pk_mul_f32 v[38:39], v[38:39], v[44:45]
	v_add_f32_e32 v44, 1.0, v46
	v_add_f32_e32 v45, 1.0, v47
	v_mul_f32_e32 v46, 0xbfb8aa3b, v42
	v_mul_f32_e32 v47, 0xbfb8aa3b, v43
	v_exp_f32_e32 v46, v46
	v_exp_f32_e32 v47, v47
	v_rcp_f32_e32 v44, v44
	v_rcp_f32_e32 v45, v45
	v_add_f32_e32 v46, 1.0, v46
	v_add_f32_e32 v47, 1.0, v47
	v_rcp_f32_e32 v46, v46
	v_rcp_f32_e32 v47, v47
	v_pk_mul_f32 v[40:41], v[40:41], v[44:45]
	v_pk_mul_f32 v[32:33], v[32:33], v[54:55] op_sel_hi:[1,0]
	v_pk_mul_f32 v[34:35], v[34:35], v[54:55] op_sel_hi:[1,0]
	v_pk_mul_f32 v[40:41], v[32:33], v[40:41]
	v_pk_mul_f32 v[32:33], v[42:43], v[46:47]
	v_add_u32_e32 v44, 0x90, v144
	v_pk_mul_f32 v[42:43], v[34:35], v[32:33]
	v_cvt_pk_bf16_f32 v32, v36, v37
	v_fmamk_f32 v36, v157, 0x3a800000, v156
	v_mul_f32_e32 v37, 0x4b800000, v36
	v_cmp_gt_f32_e32 vcc, s38, v36
	v_cvt_pk_bf16_f32 v33, v38, v39
	v_cvt_pk_bf16_f32 v34, v40, v41
	v_cndmask_b32_e32 v36, v36, v37, vcc
	v_rsq_f32_e32 v38, v36
	v_mad_i64_i32 v[36:37], s[10:11], v44, s39, v[146:147]
	v_cvt_pk_bf16_f32 v35, v42, v43
	v_mul_f32_e32 v39, 0x45800000, v38
	v_cndmask_b32_e32 v38, v38, v39, vcc
	v_pk_mul_f32 v[28:29], v[28:29], v[38:39] op_sel_hi:[1,0]
	v_lshl_add_u64 v[36:37], v[36:37], 0, v[148:149]
	v_mul_f32_e32 v39, 0xbfb8aa3b, v28
	v_exp_f32_e32 v39, v39
	v_mul_f32_e32 v40, 0xbfb8aa3b, v29
	v_exp_f32_e32 v40, v40
; #define PG8_BAR __builtin_amdgcn_s_barrier()
; DI float sigmoidf_(float v) { return __builtin_amdgcn_rcpf(1.f + __builtin_amdgcn_exp2f(-v * 1.4426950408889634f)); }
; DI u32x4 pack8(f32x4 a, f32x4 b) { u32x4 w; w.x = cvtpk(a[0], a[1]); w.y = cvtpk(a[2], a[3]); w.z = cvtpk(b[0], b[1]); w.w = cvtpk(b[2], b[3]); return w; }
; template <class Epi, class Sched, bool ALIGN_EPI = false, bool SP2 = false>
; __device__ __forceinline__ void gemm_phase(PG8_LAS unsigned char* lds, const Gemm g, const Sched& S, const Epi& E) {
;     ...
;         if constexpr (ALIGN_EPI) { if (wr == 0) PG8_BAR; }
;         if constexpr (!Epi::AFTER_DRAIN) { E(acc, cur, wr, wc, fr, fq); S.done(cur); }
;         if (!has_next) break;
; #pragma unroll
;         for (int a = 0; a < 2; ++a)
; #pragma unroll
;             for (int b = 0; b < 2; ++b)
; #pragma unroll
;                 for (int m = 0; m < 4; ++m)
; #pragma unroll
;                     for (int n = 0; n < 2; ++n) acc[a][b][m][n] = (f32x4){0.f, 0.f, 0.f, 0.f};
;         cur = nxt; cA = nA; cB = nB; ++ui;
;         if constexpr (ALIGN_EPI) { if (wr == 1) PG8_BAR; }
;   DI void operator()(const f32x4 (&acc)[2][2][4][2], const Unit& u, int wr, int wc, int fr, int fq) const {
;     ...
;       for (int m = 0; m < 4; ++m) {
;         const int row = row0 + ai * 128 + m * 16;
;         const float rstd = rsqrtf(rs[ai * 4 + m] * (1.f / DM) + EPSN);
;         f32x4 o[2];
; #pragma unroll
;         for (int n = 0; n < 2; ++n) {
;           const f32x4 a = acc[ai][0][m][n] * rstd, b = acc[ai][1][m][n] * rstd;
; #pragma unroll
;           for (int e = 0; e < 4; ++e) o[n][e] = a[e] * sigmoidf_(a[e]) * b[e];
;         }
;         __builtin_nontemporal_store(pack8(o[0], o[1]), (u32x4*)(H + (size_t)row * DFF + hcol));
	global_store_dwordx4 v[36:37], v[32:35], off nt
	v_pk_mul_f32 v[30:31], v[30:31], v[38:39] op_sel_hi:[1,0]
	v_pk_mul_f32 v[20:21], v[20:21], v[38:39] op_sel_hi:[1,0]
	v_mul_f32_e32 v34, 0xbfb8aa3b, v30
	v_mul_f32_e32 v35, 0xbfb8aa3b, v31
	v_exp_f32_e32 v34, v34
	v_exp_f32_e32 v35, v35
	v_add_f32_e32 v32, 1.0, v39
	v_add_f32_e32 v33, 1.0, v40
	v_rcp_f32_e32 v32, v32
	v_rcp_f32_e32 v33, v33
	v_add_f32_e32 v34, 1.0, v34
	v_add_f32_e32 v35, 1.0, v35
	v_rcp_f32_e32 v34, v34
	v_rcp_f32_e32 v35, v35
	v_pk_mul_f32 v[28:29], v[28:29], v[32:33]
	v_pk_mul_f32 v[24:25], v[24:25], v[38:39] op_sel_hi:[1,0]
	v_pk_mul_f32 v[20:21], v[20:21], v[28:29]
	v_pk_mul_f32 v[28:29], v[30:31], v[34:35]
	v_mul_f32_e32 v30, 0xbfb8aa3b, v24
	v_mul_f32_e32 v31, 0xbfb8aa3b, v25
	v_exp_f32_e32 v30, v30
	v_exp_f32_e32 v31, v31
	v_pk_mul_f32 v[22:23], v[22:23], v[38:39] op_sel_hi:[1,0]
	v_pk_mul_f32 v[26:27], v[26:27], v[38:39] op_sel_hi:[1,0]
	v_pk_mul_f32 v[22:23], v[22:23], v[28:29]
	v_add_f32_e32 v28, 1.0, v30
	v_add_f32_e32 v29, 1.0, v31
	v_mul_f32_e32 v30, 0xbfb8aa3b, v26
	v_mul_f32_e32 v31, 0xbfb8aa3b, v27
	v_exp_f32_e32 v30, v30
	v_exp_f32_e32 v31, v31
	v_rcp_f32_e32 v28, v28
	v_rcp_f32_e32 v29, v29
	v_add_f32_e32 v30, 1.0, v30
	v_add_f32_e32 v31, 1.0, v31
	v_rcp_f32_e32 v30, v30
	v_rcp_f32_e32 v31, v31
	v_pk_mul_f32 v[24:25], v[24:25], v[28:29]
	v_pk_mul_f32 v[16:17], v[16:17], v[38:39] op_sel_hi:[1,0]
	v_pk_mul_f32 v[18:19], v[18:19], v[38:39] op_sel_hi:[1,0]
	v_pk_mul_f32 v[24:25], v[16:17], v[24:25]
	v_pk_mul_f32 v[16:17], v[26:27], v[30:31]
	v_add_u32_e32 v28, 0xa0, v144
	v_pk_mul_f32 v[26:27], v[18:19], v[16:17]
	v_cvt_pk_bf16_f32 v16, v20, v21
	v_fmamk_f32 v20, v145, 0x3a800000, v156
	v_mul_f32_e32 v21, 0x4b800000, v20
	v_cmp_gt_f32_e32 vcc, s38, v20
	v_cvt_pk_bf16_f32 v17, v22, v23
	v_cvt_pk_bf16_f32 v18, v24, v25
	v_cndmask_b32_e32 v20, v20, v21, vcc
	v_rsq_f32_e32 v22, v20
	v_mad_i64_i32 v[20:21], s[10:11], v28, s39, v[146:147]
	v_cvt_pk_bf16_f32 v19, v26, v27
	v_mul_f32_e32 v23, 0x45800000, v22
	v_cndmask_b32_e32 v22, v22, v23, vcc
	v_pk_mul_f32 v[12:13], v[12:13], v[22:23] op_sel_hi:[1,0]
	v_lshl_add_u64 v[20:21], v[20:21], 0, v[148:149]
	v_mul_f32_e32 v23, 0xbfb8aa3b, v12
	v_exp_f32_e32 v23, v23
	v_mul_f32_e32 v24, 0xbfb8aa3b, v13
	v_exp_f32_e32 v24, v24
	global_store_dwordx4 v[20:21], v[16:19], off nt
	v_pk_mul_f32 v[14:15], v[14:15], v[22:23] op_sel_hi:[1,0]
	v_pk_mul_f32 v[4:5], v[4:5], v[22:23] op_sel_hi:[1,0]
	v_mul_f32_e32 v18, 0xbfb8aa3b, v14
	v_mul_f32_e32 v19, 0xbfb8aa3b, v15
	v_exp_f32_e32 v18, v18
	v_exp_f32_e32 v19, v19
	v_add_f32_e32 v16, 1.0, v23
	v_add_f32_e32 v17, 1.0, v24
	v_rcp_f32_e32 v16, v16
	v_rcp_f32_e32 v17, v17
	v_add_f32_e32 v18, 1.0, v18
	v_add_f32_e32 v19, 1.0, v19
	v_rcp_f32_e32 v18, v18
	v_rcp_f32_e32 v19, v19
	v_pk_mul_f32 v[12:13], v[12:13], v[16:17]
	v_pk_mul_f32 v[8:9], v[8:9], v[22:23] op_sel_hi:[1,0]
	v_pk_mul_f32 v[4:5], v[4:5], v[12:13]
	v_pk_mul_f32 v[12:13], v[14:15], v[18:19]
	v_mul_f32_e32 v14, 0xbfb8aa3b, v8
	v_mul_f32_e32 v15, 0xbfb8aa3b, v9
	v_exp_f32_e32 v14, v14
	v_exp_f32_e32 v15, v15
	v_pk_mul_f32 v[6:7], v[6:7], v[22:23] op_sel_hi:[1,0]
	v_pk_mul_f32 v[10:11], v[10:11], v[22:23] op_sel_hi:[1,0]
	v_pk_mul_f32 v[6:7], v[6:7], v[12:13]
	v_add_f32_e32 v12, 1.0, v14
	v_add_f32_e32 v13, 1.0, v15
	v_mul_f32_e32 v14, 0xbfb8aa3b, v10
	v_mul_f32_e32 v15, 0xbfb8aa3b, v11
	v_exp_f32_e32 v14, v14
	v_exp_f32_e32 v15, v15
	v_rcp_f32_e32 v12, v12
	v_rcp_f32_e32 v13, v13
	v_add_f32_e32 v14, 1.0, v14
	v_add_f32_e32 v15, 1.0, v15
	v_rcp_f32_e32 v14, v14
	v_rcp_f32_e32 v15, v15
	v_pk_mul_f32 v[8:9], v[8:9], v[12:13]
	v_pk_mul_f32 v[0:1], v[0:1], v[22:23] op_sel_hi:[1,0]
	v_pk_mul_f32 v[2:3], v[2:3], v[22:23] op_sel_hi:[1,0]
	v_pk_mul_f32 v[8:9], v[0:1], v[8:9]
	v_pk_mul_f32 v[0:1], v[10:11], v[14:15]
	v_add_u32_e32 v12, 0xb0, v144
	v_pk_mul_f32 v[10:11], v[2:3], v[0:1]
	v_cvt_pk_bf16_f32 v0, v4, v5
	v_mad_i64_i32 v[4:5], s[10:11], v12, s39, v[146:147]
	v_cvt_pk_bf16_f32 v1, v6, v7
	v_cvt_pk_bf16_f32 v2, v8, v9
	v_cvt_pk_bf16_f32 v3, v10, v11
	v_lshl_add_u64 v[4:5], v[4:5], 0, v[148:149]
	s_andn2_b64 vcc, exec, s[8:9]
	s_mov_b64 s[8:9], -1
	global_store_dwordx4 v[4:5], v[0:3], off nt
	s_cbranch_vccnz .LBB0_1249
	s_andn2_b64 vcc, exec, s[0:1]
	s_cbranch_vccnz .LBB0_1248
	s_barrier
	s_branch .LBB0_1248
